# M3 tail: waves 4..7 take row blocks 7..4 so the two waves of each SIMD share 9 causal tiles (was 6..12)
# speedup vs baseline: 1.0039x; 1.0034x over previous
; __global__ void __launch_bounds__(512, 2) fwd_megakernel(Args args) {
;     ...
;                     const int lrow = 16 * wave + r16;
;                     bf16x8 ca[4];
; #pragma unroll
;                     for (int ks = 0; ks < 4; ++ks) ca[ks] = lds_frag(Cs, lrow, 136, ks * 32 + q4 * 8);
;                     f32x4 cbr[8];
; #pragma unroll
;                     for (int st = 0; st < 8; ++st) {
;                         cbr[st] = (f32x4){0.f, 0.f, 0.f, 0.f};
;                         if (st <= wave) {
; #pragma unroll
;                             for (int ks = 0; ks < 4; ++ks) cbr[st] = mfma16(ca[ks], lds_frag(Bs, 16 * st + r16, 136, ks * 32 + q4 * 8), cbr[st]);
;                         }
;                     }
;                     __syncthreads();
; #pragma unroll 1
;                     for (int hh = 0; hh < 4; ++hh) {
;                         const int h = g2 * 4 + hh; const int unit8 = ((b * NCH + c) * 8) + h;
;                         bf16x8 pvf[4][4];
;                         {
;                             const bf16* pv = PV + (size_t)unit8 * 8192;
; #pragma unroll
;                             for (int ks = 0; ks < 4; ++ks)
; #pragma unroll
;                                 for (int pt = 0; pt < 4; ++pt) pvf[ks][pt] = *(const bf16x8*)(pv + (16 * pt + r16) * 128 + ks * 32 + q4 * 8);
;                         }
;                         bf16 zr[4][4];
; #pragma unroll
;                         for (int j = 0; j < 4; ++j)
; #pragma unroll
;                             for (int pt = 0; pt < 4; ++pt) zr[j][pt] = proj[(grow0 + 16 * wave + q4 * 4 + j) * NPROJ + PC_Z + h * 64 + 16 * pt + r16];
;                         const LAS float* hdt = s_dt + hh * 128; const LAS float* hacs = s_acs + hh * 128;
;                         float acl[4];
; #pragma unroll
;                         for (int j = 0; j < 4; ++j) acl[j] = hacs[16 * wave + q4 * 4 + j];
; #pragma unroll
;                         for (int st = 0; st < 8; ++st) {
;                             if (st <= (wave | 1)) {
;                                 const int sI = 16 * st + r16; const float acss = hacs[sI], dts = hdt[sI];
; #pragma unroll
;                                 for (int j = 0; j < 4; ++j) { const int l = 16 * wave + q4 * 4 + j; const float mv = (sI <= l) ? cbr[st][j] * __expf(fminf(acl[j] - acss, 0.f)) * dts : 0.f; Ms[l * 136 + sI] = f2bf(mv); }
.LBB0_973:
	s_waitcnt vmcnt(0) lgkmcnt(0)
	s_mov_b32 s78, s91
	s_mov_b64 s[90:91], s[92:93]
	s_mov_b64 s[92:93], s[84:85]
	s_mov_b64 s[84:85], s[94:95]
	s_mov_b64 s[96:97], s[28:29]
	s_mov_b32 s79, s59
	s_mov_b32 s33, s86
	s_lshr_b32 s2, s86, 4
	s_sub_u32 s4, 11, s2
	s_cmp_gt_u32 s2, 3
	s_cselect_b32 s2, s4, s2
	v_and_b32_e32 v176, 15, v232
	v_bfe_u32 v177, v232, 4, 2
	v_mul_u32_u24_e32 v178, 0x110, v176
	v_lshl_add_u32 v178, v177, 4, v178
	s_mul_i32 s4, s2, 0x1100
	v_add_u32_e32 v179, s4, v178
	v_readlane_b32 s24, v251, 31
	v_readlane_b32 s25, v251, 32
	v_readlane_b32 s5, v253, 58
	s_and_b32 s6, s83, 1
	s_lshl_b32 s7, s6, 2
	s_add_i32 s5, s5, s7
	s_lshl_b32 s5, s5, 2
	s_add_u32 s24, s24, s5
	s_addc_u32 s25, s25, 0
	s_load_dwordx4 s[36:39], s[24:25], 0x0
	s_lshl_b32 s7, s83, 16
	s_add_u32 s8, s80, 0x12000000
	s_addc_u32 s9, s81, 0
	s_add_u32 s8, s8, s7
	s_addc_u32 s9, s9, 0
	s_mov_b64 s[34:35], s[8:9]
	v_lshlrev_b32_e32 v196, 8, v176
	v_lshl_add_u32 v196, v177, 4, v196
	v_add_u32_e32 v197, 0x1000, v196
	v_add_u32_e32 v198, 0x2000, v196
	v_add_u32_e32 v199, 0x3000, v196
	s_lshr_b32 s7, s83, 1
	s_mul_i32 s12, s7, 0xb0000
	s_lshl_b32 s13, s6, 9
	s_add_u32 s12, s12, s13
	s_add_u32 s10, s80, 0x15000000
	s_addc_u32 s11, s81, 0
	s_add_u32 s10, s10, s12
	s_addc_u32 s11, s11, 0
	s_lshl_b32 s12, s7, 18
	s_add_u32 s12, s12, s13
	s_add_u32 s22, s80, 0xa000000
	s_addc_u32 s23, s81, 0
	s_add_u32 s12, s22, s12
	s_addc_u32 s13, s23, 0
	s_lshl_b32 s22, s6, 19
	s_lshl_b32 s23, s7, 11
	s_add_u32 s22, s22, s23
	s_add_u32 s26, s80, 0x300000
	s_addc_u32 s27, s81, 0
	s_add_u32 s22, s26, s22
	s_addc_u32 s23, s27, 0
	v_lshlrev_b32_e32 v180, 8, v176
	v_lshl_add_u32 v180, v177, 4, v180
	v_lshl_add_u32 v183, s2, 3, v177
	v_lshlrev_b32_e32 v182, 8, v183
	v_lshl_add_u32 v182, v176, 4, v182
	v_mul_u32_u24_e32 v183, 0x110, v183
	v_lshl_add_u32 v183, v176, 4, v183
	v_lshl_add_u32 v213, s2, 4, v176
	v_mul_u32_u24_e32 v184, 0x1600, v213
	v_lshl_add_u32 v184, v177, 3, v184
	v_lshlrev_b32_e32 v185, 11, v213
	v_lshl_add_u32 v185, v177, 3, v185
	v_lshlrev_b32_e32 v186, 4, v213
	v_lshlrev_b32_e32 v187, 2, v213
	v_add_u32_e32 v187, 0x22000, v187
	v_lshlrev_b32_e32 v188, 4, v177
	v_add_u32_e32 v188, 0x22000, v188
	v_mul_u32_u24_e32 v189, 0x110, v213
	v_lshl_add_u32 v189, v177, 3, v189
	v_add_u32_e32 v189, 0x8800, v189
	v_add_u32_e32 v190, 0x11000, v178
	v_mul_u32_u24_e32 v191, 0x440, v177
	v_lshl_add_u32 v191, v213, 1, v191
	v_add_u32_e32 v191, 0x11000, v191
	v_mov_b32_e32 v214, 0
	v_mov_b32_e32 v215, 0
	v_and_b32_e32 v213, 63, v232
	v_xor_b32_e32 v211, 16, v213
	v_lshlrev_b32_e32 v211, 2, v211
	v_xor_b32_e32 v212, 32, v213
	v_lshlrev_b32_e32 v212, 2, v212
	v_lshlrev_b32_e32 v213, 2, v177
	v_add_u32_e32 v160, 0, v213
	v_cmp_le_u32_e64 s[44:45], v160, v176
	v_add_u32_e32 v160, 1, v213
	v_cmp_le_u32_e64 s[46:47], v160, v176
	v_add_u32_e32 v160, 2, v213
	v_cmp_le_u32_e64 s[48:49], v160, v176
	v_add_u32_e32 v160, 3, v213
	v_cmp_le_u32_e64 s[50:51], v160, v176
	v_cmp_eq_u32_e64 s[42:43], 0, v177
	s_waitcnt vmcnt(0) lgkmcnt(0)
	s_barrier
	global_load_dwordx4 v[196:199], v182, s[8:9]
	global_load_dwordx4 v[234:237], v182, s[8:9] offset:1024
	global_load_dwordx2 v[128:129], v184, s[10:11] offset:0
	global_load_dwordx2 v[130:131], v184, s[10:11] offset:32
	global_load_dwordx2 v[132:133], v184, s[10:11] offset:64
	global_load_dwordx2 v[134:135], v184, s[10:11] offset:96
	ds_read_b128 v[32:35], v179 offset:0
	ds_read_b128 v[36:39], v179 offset:64
	ds_read_b128 v[40:43], v179 offset:128
	ds_read_b128 v[44:47], v179 offset:192
	ds_read_b128 v[160:163], v178 offset:34816
	ds_read_b128 v[164:167], v178 offset:34880
	ds_read_b128 v[168:171], v178 offset:34944
	ds_read_b128 v[172:175], v178 offset:35008
	s_cmp_lt_u32 s2, 1
	s_cbranch_scc1 .Lm3_cb_last0
	ds_read_b128 v[136:139], v178 offset:39168
	ds_read_b128 v[140:143], v178 offset:39232
	ds_read_b128 v[144:147], v178 offset:39296
	ds_read_b128 v[148:151], v178 offset:39360
	s_waitcnt lgkmcnt(4)
	v_mfma_f32_16x16x32_bf16 v[0:3], v[160:163], v[32:35], 0
	v_mfma_f32_16x16x32_bf16 v[0:3], v[164:167], v[36:39], v[0:3]
	v_mfma_f32_16x16x32_bf16 v[0:3], v[168:171], v[40:43], v[0:3]
	v_mfma_f32_16x16x32_bf16 v[0:3], v[172:175], v[44:47], v[0:3]
	s_branch .Lm3_cb_next0
